# hot loop heads (8 GEMM K-loops, 2 A loops, 4 natten loops) placed on 64-byte boundaries with .p2align 6
# speedup vs baseline: 1.0000x; 1.0000x over previous
; template <class Epi, class Sched>
; __device__ __forceinline__ void gemm_phase(LAS unsigned char* lds, const Gemm g, const Sched& S, const Epi& E) {
;     ...
;         for (int t = 0; t < nt; t += 2) {
;     ...
; #pragma unroll
;         for (int a = 0; a < 2; ++a)
; #pragma unroll
;             for (int b = 0; b < 2; ++b)
; #pragma unroll
;                 for (int m = 0; m < 4; ++m)
; #pragma unroll
;                     for (int n = 0; n < 2; ++n) acc[a][b][m][n] = (f32x4){0.f, 0.f, 0.f, 0.f};
.Lunit0_k:
	s_add_u32 s15, s0, 0x100
	s_addc_u32 s16, s1, 0
	s_add_u32 s0, s64, 0x80
	v_mov_b64_e32 v[2:3], 0
	v_mov_b64_e32 v[4:5], 0
	v_mov_b64_e32 v[6:7], 0
	v_mov_b64_e32 v[8:9], 0
	v_mov_b64_e32 v[10:11], 0
	v_mov_b64_e32 v[12:13], 0
	v_mov_b64_e32 v[14:15], 0
	v_mov_b64_e32 v[16:17], 0
	v_mov_b64_e32 v[18:19], 0
	v_mov_b64_e32 v[20:21], 0
	v_mov_b64_e32 v[22:23], 0
	v_mov_b64_e32 v[24:25], 0
	v_mov_b64_e32 v[26:27], 0
	v_mov_b64_e32 v[28:29], 0
	v_mov_b64_e32 v[30:31], 0
	v_mov_b64_e32 v[32:33], 0
	v_mov_b64_e32 v[34:35], 0
	v_mov_b64_e32 v[36:37], 0
	v_mov_b64_e32 v[38:39], 0
	v_mov_b64_e32 v[40:41], 0
	v_mov_b64_e32 v[42:43], 0
	v_mov_b64_e32 v[44:45], 0
	v_mov_b64_e32 v[46:47], 0
	v_mov_b64_e32 v[48:49], 0
	v_mov_b64_e32 v[50:51], 0
	v_mov_b64_e32 v[52:53], 0
	v_mov_b64_e32 v[54:55], 0
	v_mov_b64_e32 v[56:57], 0
	v_mov_b64_e32 v[58:59], 0
	v_mov_b64_e32 v[60:61], 0
	v_mov_b64_e32 v[62:63], 0
	v_mov_b64_e32 v[64:65], 0
	v_mov_b64_e32 v[66:67], 0
	v_mov_b64_e32 v[68:69], 0
	v_mov_b64_e32 v[70:71], 0
	v_mov_b64_e32 v[72:73], 0
	v_mov_b64_e32 v[74:75], 0
	v_mov_b64_e32 v[76:77], 0
	v_mov_b64_e32 v[78:79], 0
	v_mov_b64_e32 v[80:81], 0
	v_mov_b64_e32 v[82:83], 0
	v_mov_b64_e32 v[84:85], 0
	v_mov_b64_e32 v[86:87], 0
	v_mov_b64_e32 v[88:89], 0
	v_mov_b64_e32 v[90:91], 0
	v_mov_b64_e32 v[92:93], 0
	v_mov_b64_e32 v[94:95], 0
	v_mov_b64_e32 v[96:97], 0
	v_mov_b64_e32 v[98:99], 0
	v_mov_b64_e32 v[100:101], 0
	v_mov_b64_e32 v[102:103], 0
	v_mov_b64_e32 v[104:105], 0
	v_mov_b64_e32 v[106:107], 0
	v_mov_b64_e32 v[108:109], 0
	v_mov_b64_e32 v[110:111], 0
	v_mov_b64_e32 v[112:113], 0
	v_mov_b64_e32 v[114:115], 0
	v_mov_b64_e32 v[116:117], 0
	v_mov_b64_e32 v[118:119], 0
	v_mov_b64_e32 v[120:121], 0
	v_mov_b64_e32 v[122:123], 0
	v_mov_b64_e32 v[124:125], 0
	v_mov_b64_e32 v[126:127], 0
	v_mov_b64_e32 v[128:129], 0
	s_addc_u32 s1, s65, 0
	s_mov_b32 s28, 0
	v_add_u32_e32 v235, 0x10000, v185
	v_add_u32_e32 v238, 0x14000, v185
	v_add_u32_e32 v239, 0x18000, v185
	v_add_u32_e32 v250, 0x1c000, v185
	.p2align 6

; template <class Epi, class Sched>
; __device__ __forceinline__ void gemm_phase(LAS unsigned char* lds, const Gemm g, const Sched& S, const Epi& E) {
;     ...
;         for (int t = 0; t < nt; t += 2) {
;     ...
; #pragma unroll
;         for (int a = 0; a < 2; ++a)
; #pragma unroll
;             for (int b = 0; b < 2; ++b)
; #pragma unroll
;                 for (int m = 0; m < 4; ++m)
; #pragma unroll
;                     for (int n = 0; n < 2; ++n) acc[a][b][m][n] = (f32x4){0.f, 0.f, 0.f, 0.f};
.Lunit1_k:
	s_add_u32 s15, s0, 0x100
	s_addc_u32 s16, s1, 0
	s_add_u32 s0, s38, 0x80
	v_mov_b64_e32 v[2:3], 0
	v_mov_b64_e32 v[4:5], 0
	v_mov_b64_e32 v[6:7], 0
	v_mov_b64_e32 v[8:9], 0
	v_mov_b64_e32 v[10:11], 0
	v_mov_b64_e32 v[12:13], 0
	v_mov_b64_e32 v[14:15], 0
	v_mov_b64_e32 v[16:17], 0
	v_mov_b64_e32 v[18:19], 0
	v_mov_b64_e32 v[20:21], 0
	v_mov_b64_e32 v[22:23], 0
	v_mov_b64_e32 v[24:25], 0
	v_mov_b64_e32 v[26:27], 0
	v_mov_b64_e32 v[28:29], 0
	v_mov_b64_e32 v[30:31], 0
	v_mov_b64_e32 v[32:33], 0
	v_mov_b64_e32 v[34:35], 0
	v_mov_b64_e32 v[36:37], 0
	v_mov_b64_e32 v[38:39], 0
	v_mov_b64_e32 v[40:41], 0
	v_mov_b64_e32 v[42:43], 0
	v_mov_b64_e32 v[44:45], 0
	v_mov_b64_e32 v[46:47], 0
	v_mov_b64_e32 v[48:49], 0
	v_mov_b64_e32 v[50:51], 0
	v_mov_b64_e32 v[52:53], 0
	v_mov_b64_e32 v[54:55], 0
	v_mov_b64_e32 v[56:57], 0
	v_mov_b64_e32 v[58:59], 0
	v_mov_b64_e32 v[60:61], 0
	v_mov_b64_e32 v[62:63], 0
	v_mov_b64_e32 v[64:65], 0
	v_mov_b64_e32 v[66:67], 0
	v_mov_b64_e32 v[68:69], 0
	v_mov_b64_e32 v[70:71], 0
	v_mov_b64_e32 v[72:73], 0
	v_mov_b64_e32 v[74:75], 0
	v_mov_b64_e32 v[76:77], 0
	v_mov_b64_e32 v[78:79], 0
	v_mov_b64_e32 v[80:81], 0
	v_mov_b64_e32 v[82:83], 0
	v_mov_b64_e32 v[84:85], 0
	v_mov_b64_e32 v[86:87], 0
	v_mov_b64_e32 v[88:89], 0
	v_mov_b64_e32 v[90:91], 0
	v_mov_b64_e32 v[92:93], 0
	v_mov_b64_e32 v[94:95], 0
	v_mov_b64_e32 v[96:97], 0
	v_mov_b64_e32 v[98:99], 0
	v_mov_b64_e32 v[100:101], 0
	v_mov_b64_e32 v[102:103], 0
	v_mov_b64_e32 v[104:105], 0
	v_mov_b64_e32 v[106:107], 0
	v_mov_b64_e32 v[108:109], 0
	v_mov_b64_e32 v[110:111], 0
	v_mov_b64_e32 v[112:113], 0
	v_mov_b64_e32 v[114:115], 0
	v_mov_b64_e32 v[116:117], 0
	v_mov_b64_e32 v[118:119], 0
	v_mov_b64_e32 v[120:121], 0
	v_mov_b64_e32 v[122:123], 0
	v_mov_b64_e32 v[124:125], 0
	v_mov_b64_e32 v[126:127], 0
	v_mov_b64_e32 v[128:129], 0
	s_addc_u32 s1, s39, 0
	s_mov_b32 s28, 0
	v_add_u32_e32 v235, 0x10000, v217
	v_add_u32_e32 v238, 0x14000, v217
	v_add_u32_e32 v239, 0x18000, v217
	v_add_u32_e32 v250, 0x1c000, v217
	.p2align 6

; template <class Epi, class Sched>
; __device__ __forceinline__ void gemm_phase(LAS unsigned char* lds, const Gemm g, const Sched& S, const Epi& E) {
;     ...
;         for (int t = 0; t < nt; t += 2) {
;     ...
; #pragma unroll
;         for (int a = 0; a < 2; ++a)
; #pragma unroll
;             for (int b = 0; b < 2; ++b)
; #pragma unroll
;                 for (int m = 0; m < 4; ++m)
; #pragma unroll
;                     for (int n = 0; n < 2; ++n) acc[a][b][m][n] = (f32x4){0.f, 0.f, 0.f, 0.f};
.Lunit2_k:
	s_add_u32 s15, s0, 0x100
	s_addc_u32 s16, s1, 0
	s_add_u32 s0, s38, 0x80
	v_mov_b64_e32 v[2:3], 0
	v_mov_b64_e32 v[4:5], 0
	v_mov_b64_e32 v[6:7], 0
	v_mov_b64_e32 v[8:9], 0
	v_mov_b64_e32 v[10:11], 0
	v_mov_b64_e32 v[12:13], 0
	v_mov_b64_e32 v[14:15], 0
	v_mov_b64_e32 v[16:17], 0
	v_mov_b64_e32 v[18:19], 0
	v_mov_b64_e32 v[20:21], 0
	v_mov_b64_e32 v[22:23], 0
	v_mov_b64_e32 v[24:25], 0
	v_mov_b64_e32 v[26:27], 0
	v_mov_b64_e32 v[28:29], 0
	v_mov_b64_e32 v[30:31], 0
	v_mov_b64_e32 v[32:33], 0
	v_mov_b64_e32 v[34:35], 0
	v_mov_b64_e32 v[36:37], 0
	v_mov_b64_e32 v[38:39], 0
	v_mov_b64_e32 v[40:41], 0
	v_mov_b64_e32 v[42:43], 0
	v_mov_b64_e32 v[44:45], 0
	v_mov_b64_e32 v[46:47], 0
	v_mov_b64_e32 v[48:49], 0
	v_mov_b64_e32 v[50:51], 0
	v_mov_b64_e32 v[52:53], 0
	v_mov_b64_e32 v[54:55], 0
	v_mov_b64_e32 v[56:57], 0
	v_mov_b64_e32 v[58:59], 0
	v_mov_b64_e32 v[60:61], 0
	v_mov_b64_e32 v[62:63], 0
	v_mov_b64_e32 v[64:65], 0
	v_mov_b64_e32 v[66:67], 0
	v_mov_b64_e32 v[68:69], 0
	v_mov_b64_e32 v[70:71], 0
	v_mov_b64_e32 v[72:73], 0
	v_mov_b64_e32 v[74:75], 0
	v_mov_b64_e32 v[76:77], 0
	v_mov_b64_e32 v[78:79], 0
	v_mov_b64_e32 v[80:81], 0
	v_mov_b64_e32 v[82:83], 0
	v_mov_b64_e32 v[84:85], 0
	v_mov_b64_e32 v[86:87], 0
	v_mov_b64_e32 v[88:89], 0
	v_mov_b64_e32 v[90:91], 0
	v_mov_b64_e32 v[92:93], 0
	v_mov_b64_e32 v[94:95], 0
	v_mov_b64_e32 v[96:97], 0
	v_mov_b64_e32 v[98:99], 0
	v_mov_b64_e32 v[100:101], 0
	v_mov_b64_e32 v[102:103], 0
	v_mov_b64_e32 v[104:105], 0
	v_mov_b64_e32 v[106:107], 0
	v_mov_b64_e32 v[108:109], 0
	v_mov_b64_e32 v[110:111], 0
	v_mov_b64_e32 v[112:113], 0
	v_mov_b64_e32 v[114:115], 0
	v_mov_b64_e32 v[116:117], 0
	v_mov_b64_e32 v[118:119], 0
	v_mov_b64_e32 v[120:121], 0
	v_mov_b64_e32 v[122:123], 0
	v_mov_b64_e32 v[124:125], 0
	v_mov_b64_e32 v[126:127], 0
	v_mov_b64_e32 v[128:129], 0
	s_addc_u32 s1, s39, 0
	s_mov_b32 s28, 0
	v_add_u32_e32 v235, 0x10000, v185
	v_add_u32_e32 v238, 0x14000, v185
	v_add_u32_e32 v239, 0x18000, v185
	v_add_u32_e32 v250, 0x1c000, v185
	.p2align 6

; #define A_ISSUE(t) do { int tok_ = 64 * (t) + lrow; tok_ = tok_ > LT - 1 ? LT - 1 : tok_; const bf16_t* src_ = pb + (size_t)tok_ * INC; \
;         pre[0] = *(const u32x4*)(src_ + 512); pre[1] = *(const u32x4*)(src_ + 576); pre[2] = *(const u32x4*)(src_ + 1024); pre[3] = *(const u32x4*)(src_ + 1088); } while (0)
; #define A_WRITE(bufo) do { LAS char* d_ = lds + (bufo); \
;         *(LAS u32x4*)(d_ + lrow * AKP + lch * 16) = pre[0]; *(LAS u32x4*)(d_ + AKS + lrow * AKP + lch * 16) = pre[1]; \
;         *(LAS u32x4*)(d_ + 2 * AKS + lrow * AVP + lch * 16) = pre[2]; *(LAS u32x4*)(d_ + 2 * AKS + AVS + lrow * AVP + lch * 16) = pre[3]; } while (0)
; #define A_BAR() asm volatile("s_waitcnt lgkmcnt(0)\n\ts_barrier" ::: "memory")
; __device__ __forceinline__ void attn_unit_A(const AttnP& P, int u, LAS char* lds) {
;     ...
;     A_ISSUE(0);
;     __syncthreads();
;     A_WRITE(0); A_ISSUE(1);
;     A_BAR();
;     f32x16 sa0, sa1, negc; float lrun = 0.f;
;     ...
;     int bcur = 0, bnext = ABUF;
;     for (int t = 0; t < nt; ++t) {
;         const bool more = (t + 1 < nt);
;         if (more) { A_WRITE(bnext); if (t + 2 < nt) A_ISSUE(t + 2); }
.LBB0_656:
	v_add3_u32 v238, s29, v178, v160
	v_add3_u32 v239, s29, v180, v160
	s_waitcnt vmcnt(3)
	ds_write_b128 v238, v[156:159]
	s_waitcnt vmcnt(2)
	ds_write_b128 v238, v[152:155] offset:9216
	s_waitcnt vmcnt(1)
	ds_write_b128 v239, v[148:151] offset:18432
	s_waitcnt vmcnt(0)
	ds_write_b128 v239, v[144:147] offset:30720
	v_add_u32_e32 v238, s35, v181
	v_min_i32_e32 v238, 0x100f, v238
	v_mad_i64_i32 v[192:193], s[0:1], v238, s51, v[162:163]
	global_load_dwordx4 v[156:159], v[192:193], off offset:1024
	global_load_dwordx4 v[152:155], v[192:193], off offset:1152
	global_load_dwordx4 v[148:151], v[192:193], off offset:2048
	global_load_dwordx4 v[144:147], v[192:193], off offset:2176
	v_mov_b32_e32 v206, v96
	v_mov_b32_e32 v0, v112
	v_mov_b32_e32 v207, v97
	v_mov_b32_e32 v1, v113
	v_mov_b32_e32 v208, v98
	v_mov_b32_e32 v2, v114
	v_mov_b32_e32 v209, v99
	v_mov_b32_e32 v3, v115
	v_mov_b32_e32 v210, v100
	v_mov_b32_e32 v4, v116
	v_mov_b32_e32 v211, v101
	v_mov_b32_e32 v5, v117
	v_mov_b32_e32 v212, v102
	v_mov_b32_e32 v6, v118
	v_mov_b32_e32 v213, v103
	v_mov_b32_e32 v7, v119
	v_mov_b32_e32 v214, v104
	v_mov_b32_e32 v8, v120
	v_mov_b32_e32 v215, v105
	v_mov_b32_e32 v9, v121
	v_mov_b32_e32 v216, v106
	v_mov_b32_e32 v10, v122
	v_mov_b32_e32 v217, v107
	v_mov_b32_e32 v11, v123
	v_mov_b32_e32 v218, v108
	v_mov_b32_e32 v12, v124
	v_mov_b32_e32 v219, v109
	v_mov_b32_e32 v13, v125
	v_mov_b32_e32 v220, v110
	v_mov_b32_e32 v14, v126
	v_mov_b32_e32 v221, v111
	v_mov_b32_e32 v15, v127
	v_mov_b32_e32 v202, 0
	s_mov_b32 s38, 0x15000
	s_waitcnt lgkmcnt(0)
	s_barrier
	.p2align 6

; #define A_ISSUE(t) do { int tok_ = 64 * (t) + lrow; tok_ = tok_ > LT - 1 ? LT - 1 : tok_; const bf16_t* src_ = pb + (size_t)tok_ * INC; \
;         pre[0] = *(const u32x4*)(src_ + 512); pre[1] = *(const u32x4*)(src_ + 576); pre[2] = *(const u32x4*)(src_ + 1024); pre[3] = *(const u32x4*)(src_ + 1088); } while (0)
; #define A_WRITE(bufo) do { LAS char* d_ = lds + (bufo); \
;         *(LAS u32x4*)(d_ + lrow * AKP + lch * 16) = pre[0]; *(LAS u32x4*)(d_ + AKS + lrow * AKP + lch * 16) = pre[1]; \
;         *(LAS u32x4*)(d_ + 2 * AKS + lrow * AVP + lch * 16) = pre[2]; *(LAS u32x4*)(d_ + 2 * AKS + AVS + lrow * AVP + lch * 16) = pre[3]; } while (0)
; #define A_BAR() asm volatile("s_waitcnt lgkmcnt(0)\n\ts_barrier" ::: "memory")
; __device__ __forceinline__ void attn_unit_A(const AttnP& P, int u, LAS char* lds) {
;     ...
;     A_ISSUE(0);
;     __syncthreads();
;     A_WRITE(0); A_ISSUE(1);
;     A_BAR();
;     f32x16 sa0, sa1, negc; float lrun = 0.f;
;     ...
;     int bcur = 0, bnext = ABUF;
;     for (int t = 0; t < nt; ++t) {
;         const bool more = (t + 1 < nt);
;         if (more) { A_WRITE(bnext); if (t + 2 < nt) A_ISSUE(t + 2); }
.LBB0_749:
	v_add3_u32 v238, s28, v172, v160
	v_add3_u32 v239, s28, v174, v160
	s_waitcnt vmcnt(3)
	ds_write_b128 v238, v[156:159]
	s_waitcnt vmcnt(2)
	ds_write_b128 v238, v[152:155] offset:9216
	s_waitcnt vmcnt(1)
	ds_write_b128 v239, v[148:151] offset:18432
	s_waitcnt vmcnt(0)
	ds_write_b128 v239, v[144:147] offset:30720
	v_add_u32_e32 v238, s31, v175
	v_min_i32_e32 v238, 0x100f, v238
	v_mad_i64_i32 v[244:245], s[0:1], v238, s51, v[162:163]
	global_load_dwordx4 v[156:159], v[244:245], off offset:1024
	global_load_dwordx4 v[152:155], v[244:245], off offset:1152
	global_load_dwordx4 v[148:151], v[244:245], off offset:2048
	global_load_dwordx4 v[144:147], v[244:245], off offset:2176
	v_mov_b32_e32 v206, v96
	v_mov_b32_e32 v0, v112
	v_mov_b32_e32 v207, v97
	v_mov_b32_e32 v1, v113
	v_mov_b32_e32 v208, v98
	v_mov_b32_e32 v2, v114
	v_mov_b32_e32 v209, v99
	v_mov_b32_e32 v3, v115
	v_mov_b32_e32 v210, v100
	v_mov_b32_e32 v4, v116
	v_mov_b32_e32 v211, v101
	v_mov_b32_e32 v5, v117
	v_mov_b32_e32 v212, v102
	v_mov_b32_e32 v6, v118
	v_mov_b32_e32 v213, v103
	v_mov_b32_e32 v7, v119
	v_mov_b32_e32 v214, v104
	v_mov_b32_e32 v8, v120
	v_mov_b32_e32 v215, v105
	v_mov_b32_e32 v9, v121
	v_mov_b32_e32 v216, v106
	v_mov_b32_e32 v10, v122
	v_mov_b32_e32 v217, v107
	v_mov_b32_e32 v11, v123
	v_mov_b32_e32 v218, v108
	v_mov_b32_e32 v12, v124
	v_mov_b32_e32 v219, v109
	v_mov_b32_e32 v13, v125
	v_mov_b32_e32 v220, v110
	v_mov_b32_e32 v14, v126
	v_mov_b32_e32 v221, v111
	v_mov_b32_e32 v15, v127
	v_mov_b32_e32 v202, 0
	s_mov_b32 s35, 0x15000
	s_waitcnt lgkmcnt(0)
	s_barrier
	.p2align 6

; #define LAS __attribute__((address_space(3)))
; template <int MODE> __device__ __forceinline__ void attn_unit(const AttnP& P, int u, LAS char* lds, bool fill) {
;     ...
;                 const int roff = (rs_ + t - 1) - x2 + 7;
;                 const LAS float* rt = metaunit ? tab + 4 * 593 + 4 * hi : mytab + roff * 31 + 15 - ccol + 4 * hi;
; #pragma unroll
;                 for (int r = 0; r < 16; ++r) { p0[r] = p0[r] + rt[(r & 3) + 8 * (r >> 2)] + ng0[r]; p1[r] = p1[r] + rt[(r & 3) + 8 * (r >> 2) + 32] + ng1[r]; }
;     ...
;             const float mnew = fmaxf(mrun, mx); const float f = __builtin_amdgcn_exp2f(mrun - mnew); mrun = mnew; lrun *= f;
.Lnat1L_entry:
	v_sub_f32_e32 v133, v133, v167
	v_sub_f32_e32 v135, v135, v167
	v_sub_f32_e32 v137, v137, v167
	v_sub_f32_e32 v139, v139, v167
	v_sub_f32_e32 v141, v141, v167
	v_sub_f32_e32 v143, v143, v167
	v_sub_f32_e32 v145, v145, v167
	v_sub_f32_e32 v147, v147, v167
	v_sub_f32_e32 v149, v149, v167
	v_sub_f32_e32 v151, v151, v167
	v_sub_f32_e32 v153, v153, v167
	v_sub_f32_e32 v155, v155, v167
	v_sub_f32_e32 v157, v157, v167
	v_sub_f32_e32 v159, v159, v167
	v_sub_f32_e32 v161, v161, v167
	v_sub_f32_e32 v163, v163, v167
	v_sub_f32_e32 v134, v134, v167
	v_sub_f32_e32 v136, v136, v167
	v_sub_f32_e32 v138, v138, v167
	v_sub_f32_e32 v140, v140, v167
	.p2align 6

; #define LAS __attribute__((address_space(3)))
; template <int MODE> __device__ __forceinline__ void attn_unit(const AttnP& P, int u, LAS char* lds, bool fill) {
;     ...
;                 const int roff = (rs_ + t - 1) - x2 + 7;
;                 const LAS float* rt = metaunit ? tab + 4 * 593 + 4 * hi : mytab + roff * 31 + 15 - ccol + 4 * hi;
; #pragma unroll
;                 for (int r = 0; r < 16; ++r) { p0[r] = p0[r] + rt[(r & 3) + 8 * (r >> 2)] + ng0[r]; p1[r] = p1[r] + rt[(r & 3) + 8 * (r >> 2) + 32] + ng1[r]; }
;     ...
;             const float mnew = fmaxf(mrun, mx); const float f = __builtin_amdgcn_exp2f(mrun - mnew); mrun = mnew; lrun *= f;
.Lnat1R_entry:
	v_sub_f32_e32 v157, v157, v167
	v_sub_f32_e32 v159, v159, v167
	v_sub_f32_e32 v161, v161, v167
	v_sub_f32_e32 v163, v163, v167
	v_sub_f32_e32 v134, v134, v167
	v_sub_f32_e32 v136, v136, v167
	v_sub_f32_e32 v138, v138, v167
	v_sub_f32_e32 v140, v140, v167
	v_sub_f32_e32 v142, v142, v167
	v_sub_f32_e32 v144, v144, v167
	v_sub_f32_e32 v146, v146, v167
	v_sub_f32_e32 v148, v148, v167
	v_sub_f32_e32 v150, v150, v167
	v_sub_f32_e32 v152, v152, v167
	v_sub_f32_e32 v154, v154, v167
	v_sub_f32_e32 v156, v156, v167
	v_sub_f32_e32 v158, v158, v167
	v_sub_f32_e32 v160, v160, v167
	v_sub_f32_e32 v162, v162, v167
	v_sub_f32_e32 v164, v164, v167
	.p2align 6

; template <class Epi, class Sched>
; __device__ __forceinline__ void gemm_phase(LAS unsigned char* lds, const Gemm g, const Sched& S, const Epi& E) {
;     ...
;         for (int t = 0; t < nt; t += 2) {
;             const bool last = (t == nt - 2);
;             const char* a1 = cA + (size_t)(t + 1) * kstep;
;             const char* a2 = last ? nA : cA + (size_t)(t + 2) * kstep; const char* b2 = last ? nB : cB + (size_t)(t + 2) * kstep;
;             const char* a3 = a2 + kstep; const char* b3 = b2 + kstep;
;     ...
; #pragma unroll
;         for (int a = 0; a < 2; ++a)
; #pragma unroll
;             for (int b = 0; b < 2; ++b)
; #pragma unroll
;                 for (int m = 0; m < 4; ++m)
; #pragma unroll
;                     for (int n = 0; n < 2; ++n) acc[a][b][m][n] = (f32x4){0.f, 0.f, 0.f, 0.f};
;         cur = nxt; cA = nA; cB = nB; ++ui;
.Lunit4_k:
	s_add_u32 s15, s0, 0x100
	s_addc_u32 s16, s1, 0
	s_add_u32 s0, s38, 0x80
	v_mov_b64_e32 v[2:3], 0
	v_mov_b64_e32 v[4:5], 0
	v_mov_b64_e32 v[6:7], 0
	v_mov_b64_e32 v[8:9], 0
	v_mov_b64_e32 v[10:11], 0
	v_mov_b64_e32 v[12:13], 0
	v_mov_b64_e32 v[14:15], 0
	v_mov_b64_e32 v[16:17], 0
	v_mov_b64_e32 v[18:19], 0
	v_mov_b64_e32 v[20:21], 0
	v_mov_b64_e32 v[22:23], 0
	v_mov_b64_e32 v[24:25], 0
	v_mov_b64_e32 v[26:27], 0
	v_mov_b64_e32 v[28:29], 0
	v_mov_b64_e32 v[30:31], 0
	v_mov_b64_e32 v[32:33], 0
	v_mov_b64_e32 v[34:35], 0
	v_mov_b64_e32 v[36:37], 0
	v_mov_b64_e32 v[38:39], 0
	v_mov_b64_e32 v[40:41], 0
	v_mov_b64_e32 v[42:43], 0
	v_mov_b64_e32 v[44:45], 0
	v_mov_b64_e32 v[46:47], 0
	v_mov_b64_e32 v[48:49], 0
	v_mov_b64_e32 v[50:51], 0
	v_mov_b64_e32 v[52:53], 0
	v_mov_b64_e32 v[54:55], 0
	v_mov_b64_e32 v[56:57], 0
	v_mov_b64_e32 v[58:59], 0
	v_mov_b64_e32 v[60:61], 0
	v_mov_b64_e32 v[62:63], 0
	v_mov_b64_e32 v[64:65], 0
	v_mov_b64_e32 v[66:67], 0
	v_mov_b64_e32 v[68:69], 0
	v_mov_b64_e32 v[70:71], 0
	v_mov_b64_e32 v[72:73], 0
	v_mov_b64_e32 v[74:75], 0
	v_mov_b64_e32 v[76:77], 0
	v_mov_b64_e32 v[78:79], 0
	v_mov_b64_e32 v[80:81], 0
	v_mov_b64_e32 v[82:83], 0
	v_mov_b64_e32 v[84:85], 0
	v_mov_b64_e32 v[86:87], 0
	v_mov_b64_e32 v[88:89], 0
	v_mov_b64_e32 v[90:91], 0
	v_mov_b64_e32 v[92:93], 0
	v_mov_b64_e32 v[94:95], 0
	v_mov_b64_e32 v[96:97], 0
	v_mov_b64_e32 v[98:99], 0
	v_mov_b64_e32 v[100:101], 0
	v_mov_b64_e32 v[102:103], 0
	v_mov_b64_e32 v[104:105], 0
	v_mov_b64_e32 v[106:107], 0
	v_mov_b64_e32 v[108:109], 0
	v_mov_b64_e32 v[110:111], 0
	v_mov_b64_e32 v[112:113], 0
	v_mov_b64_e32 v[114:115], 0
	v_mov_b64_e32 v[116:117], 0
	v_mov_b64_e32 v[118:119], 0
	v_mov_b64_e32 v[120:121], 0
	v_mov_b64_e32 v[122:123], 0
	v_mov_b64_e32 v[124:125], 0
	v_mov_b64_e32 v[126:127], 0
	v_mov_b64_e32 v[128:129], 0
	s_addc_u32 s1, s39, 0
	s_mov_b32 s28, 0
	.p2align 6

; template <class Epi, class Sched>
; __device__ __forceinline__ void gemm_phase(LAS unsigned char* lds, const Gemm g, const Sched& S, const Epi& E) {
;     ...
;         for (int t = 0; t < nt; t += 2) {
;             const bool last = (t == nt - 2);
;             const char* a1 = cA + (size_t)(t + 1) * kstep;
;             const char* a2 = last ? nA : cA + (size_t)(t + 2) * kstep; const char* b2 = last ? nB : cB + (size_t)(t + 2) * kstep;
;             const char* a3 = a2 + kstep; const char* b3 = b2 + kstep;
;     ...
; #pragma unroll
;         for (int a = 0; a < 2; ++a)
; #pragma unroll
;             for (int b = 0; b < 2; ++b)
; #pragma unroll
;                 for (int m = 0; m < 4; ++m)
; #pragma unroll
;                     for (int n = 0; n < 2; ++n) acc[a][b][m][n] = (f32x4){0.f, 0.f, 0.f, 0.f};
;         cur = nxt; cA = nA; cB = nB; ++ui;
.Lunit7_k:
	s_add_u32 s15, s0, 0x100
	s_addc_u32 s16, s1, 0
	s_add_u32 s0, s64, 0x80
	v_mov_b64_e32 v[2:3], 0
	v_mov_b64_e32 v[4:5], 0
	v_mov_b64_e32 v[6:7], 0
	v_mov_b64_e32 v[8:9], 0
	v_mov_b64_e32 v[10:11], 0
	v_mov_b64_e32 v[12:13], 0
	v_mov_b64_e32 v[14:15], 0
	v_mov_b64_e32 v[16:17], 0
	v_mov_b64_e32 v[18:19], 0
	v_mov_b64_e32 v[20:21], 0
	v_mov_b64_e32 v[22:23], 0
	v_mov_b64_e32 v[24:25], 0
	v_mov_b64_e32 v[26:27], 0
	v_mov_b64_e32 v[28:29], 0
	v_mov_b64_e32 v[30:31], 0
	v_mov_b64_e32 v[32:33], 0
	v_mov_b64_e32 v[34:35], 0
	v_mov_b64_e32 v[36:37], 0
	v_mov_b64_e32 v[38:39], 0
	v_mov_b64_e32 v[40:41], 0
	v_mov_b64_e32 v[42:43], 0
	v_mov_b64_e32 v[44:45], 0
	v_mov_b64_e32 v[46:47], 0
	v_mov_b64_e32 v[48:49], 0
	v_mov_b64_e32 v[50:51], 0
	v_mov_b64_e32 v[52:53], 0
	v_mov_b64_e32 v[54:55], 0
	v_mov_b64_e32 v[56:57], 0
	v_mov_b64_e32 v[58:59], 0
	v_mov_b64_e32 v[60:61], 0
	v_mov_b64_e32 v[62:63], 0
	v_mov_b64_e32 v[64:65], 0
	v_mov_b64_e32 v[66:67], 0
	v_mov_b64_e32 v[68:69], 0
	v_mov_b64_e32 v[70:71], 0
	v_mov_b64_e32 v[72:73], 0
	v_mov_b64_e32 v[74:75], 0
	v_mov_b64_e32 v[76:77], 0
	v_mov_b64_e32 v[78:79], 0
	v_mov_b64_e32 v[80:81], 0
	v_mov_b64_e32 v[82:83], 0
	v_mov_b64_e32 v[84:85], 0
	v_mov_b64_e32 v[86:87], 0
	v_mov_b64_e32 v[88:89], 0
	v_mov_b64_e32 v[90:91], 0
	v_mov_b64_e32 v[92:93], 0
	v_mov_b64_e32 v[94:95], 0
	v_mov_b64_e32 v[96:97], 0
	v_mov_b64_e32 v[98:99], 0
	v_mov_b64_e32 v[100:101], 0
	v_mov_b64_e32 v[102:103], 0
	v_mov_b64_e32 v[104:105], 0
	v_mov_b64_e32 v[106:107], 0
	v_mov_b64_e32 v[108:109], 0
	v_mov_b64_e32 v[110:111], 0
	v_mov_b64_e32 v[112:113], 0
	v_mov_b64_e32 v[114:115], 0
	v_mov_b64_e32 v[116:117], 0
	v_mov_b64_e32 v[118:119], 0
	v_mov_b64_e32 v[120:121], 0
	v_mov_b64_e32 v[122:123], 0
	v_mov_b64_e32 v[124:125], 0
	v_mov_b64_e32 v[126:127], 0
	v_mov_b64_e32 v[128:129], 0
	s_addc_u32 s1, s65, 0
	s_mov_b32 s28, 0
	v_add_u32_e32 v235, 0x10000, v217
	v_add_u32_e32 v238, 0x14000, v217
	v_add_u32_e32 v239, 0x18000, v217
	v_add_u32_e32 v250, 0x1c000, v217
	.p2align 6
